# SwiGLU epilogue math rewritten: ((g*u)*ri^2)*rcp(1+exp2(g*ri*-log2e)), 10 VALU per output pair, no hazard nops
# speedup vs baseline: 1.0204x; 1.0171x over previous
; __device__ __forceinline__ unsigned cvt_pk_bf16(float lo, float hi) { bf16v2_t r = __builtin_convertvector((f32x2_t){lo, hi}, bf16v2_t); return __builtin_bit_cast(unsigned, r); }
; __device__ __forceinline__ float sigm(float x) { return __builtin_amdgcn_rcpf(1.0f + __expf(-x)); }
;     __device__ __forceinline__ void operator()(const f32x4 (&acc)[2][2][4][2], const Unit& u, int wr, int wc, int fr, int fq) const {
;         const int row0 = u.pm * BM + wr * 64 + fr, col0 = u.pn * HALF + wc * 32 + 8 * fq;
;         RowRinv8 rr; rr.load(ssq, row0, fq, u.pm, lds);
; #pragma unroll
;         for (int ai = 0; ai < 2; ++ai)
; #pragma unroll
;             for (int m = 0; m < 4; ++m) {
;                 bf16_t* rowp = O + (size_t)(row0 + ai * HALF + m * 16) * ldc + col0;
;                 const float ri = rr.get(ai, m);
;                 float r[8];
; #pragma unroll
;                 for (int n = 0; n < 2; ++n)
; #pragma unroll
;                     for (int j = 0; j < 4; ++j) { const float g = acc[ai][0][m][n][j] * ri, up = acc[ai][1][m][n][j] * ri; r[n * 4 + j] = g * sigm(g) * up; }
;                 u32x4 w; w.x = cvt_pk_bf16(r[0], r[1]); w.y = cvt_pk_bf16(r[2], r[3]); w.z = cvt_pk_bf16(r[4], r[5]); w.w = cvt_pk_bf16(r[6], r[7]);
;                 *(u32x4*)rowp = w;
.LBB0_264:
	s_or_b64 exec, exec, s[8:9]
	v_readlane_b32 s8, v252, 30
	v_readlane_b32 s9, v252, 31
	s_movk_i32 s13, 0x1600
	v_mov_b32_e32 v218, 1.0
	v_mov_b32_e32 v219, 1.0
	v_lshl_or_b32 v250, s51, 7, v211
	v_ashrrev_i32_e32 v251, 31, v250
	v_lshl_add_u64 v[248:249], v[250:251], 1, s[8:9]
	v_mul_f32_e32 v220, 0xbfb8aa3b, v140
	v_mul_f32_e32 v222, v140, v140
	v_pk_mul_f32 v[224:225], v[136:137], v[220:221] op_sel_hi:[1,0]
	v_pk_mul_f32 v[226:227], v[138:139], v[220:221] op_sel_hi:[1,0]
	v_pk_mul_f32 v[228:229], v[128:129], v[220:221] op_sel_hi:[1,0]
	v_pk_mul_f32 v[230:231], v[130:131], v[220:221] op_sel_hi:[1,0]
	v_mad_u64_u32 v[250:251], s[8:9], v200, s13, v[248:249]
	v_exp_f32_e32 v224, v224
	v_exp_f32_e32 v225, v225
	v_exp_f32_e32 v226, v226
	v_exp_f32_e32 v227, v227
	v_exp_f32_e32 v228, v228
	v_exp_f32_e32 v229, v229
	v_exp_f32_e32 v230, v230
	v_exp_f32_e32 v231, v231
	v_pk_mul_f32 v[232:233], v[136:137], v[132:133]
	v_pk_mul_f32 v[234:235], v[138:139], v[134:135]
	v_pk_mul_f32 v[236:237], v[128:129], v[124:125]
	v_pk_mul_f32 v[238:239], v[130:131], v[126:127]
	v_pk_add_f32 v[224:225], v[224:225], v[218:219]
	v_pk_add_f32 v[226:227], v[226:227], v[218:219]
	v_pk_add_f32 v[228:229], v[228:229], v[218:219]
	v_pk_add_f32 v[230:231], v[230:231], v[218:219]
	v_rcp_f32_e32 v224, v224
	v_rcp_f32_e32 v225, v225
	v_rcp_f32_e32 v226, v226
	v_rcp_f32_e32 v227, v227
	v_rcp_f32_e32 v228, v228
	v_rcp_f32_e32 v229, v229
	v_rcp_f32_e32 v230, v230
	v_rcp_f32_e32 v231, v231
	v_pk_mul_f32 v[232:233], v[232:233], v[222:223] op_sel_hi:[1,0]
	v_pk_mul_f32 v[234:235], v[234:235], v[222:223] op_sel_hi:[1,0]
	v_pk_mul_f32 v[236:237], v[236:237], v[222:223] op_sel_hi:[1,0]
	v_pk_mul_f32 v[238:239], v[238:239], v[222:223] op_sel_hi:[1,0]
	v_pk_mul_f32 v[232:233], v[232:233], v[224:225]
	v_pk_mul_f32 v[234:235], v[234:235], v[226:227]
	v_pk_mul_f32 v[236:237], v[236:237], v[228:229]
	v_pk_mul_f32 v[238:239], v[238:239], v[230:231]
	v_cvt_pk_bf16_f32 v240, v232, v233
	v_cvt_pk_bf16_f32 v241, v234, v235
	v_cvt_pk_bf16_f32 v242, v236, v237
	v_cvt_pk_bf16_f32 v243, v238, v239
	global_store_dwordx4 v[250:251], v[240:243], off
	v_mul_f32_e32 v220, 0xbfb8aa3b, v148
	v_mul_f32_e32 v222, v148, v148
	v_pk_mul_f32 v[224:225], v[120:121], v[220:221] op_sel_hi:[1,0]
	v_pk_mul_f32 v[226:227], v[122:123], v[220:221] op_sel_hi:[1,0]
	v_pk_mul_f32 v[228:229], v[112:113], v[220:221] op_sel_hi:[1,0]
	v_pk_mul_f32 v[230:231], v[114:115], v[220:221] op_sel_hi:[1,0]
	v_mad_u64_u32 v[250:251], s[8:9], v198, s13, v[248:249]
	v_exp_f32_e32 v224, v224
	v_exp_f32_e32 v225, v225
	v_exp_f32_e32 v226, v226
	v_exp_f32_e32 v227, v227
	v_exp_f32_e32 v228, v228
	v_exp_f32_e32 v229, v229
	v_exp_f32_e32 v230, v230
	v_exp_f32_e32 v231, v231
	v_pk_mul_f32 v[232:233], v[120:121], v[116:117]
	v_pk_mul_f32 v[234:235], v[122:123], v[118:119]
	v_pk_mul_f32 v[236:237], v[112:113], v[108:109]
	v_pk_mul_f32 v[238:239], v[114:115], v[110:111]
	v_pk_add_f32 v[224:225], v[224:225], v[218:219]
	v_pk_add_f32 v[226:227], v[226:227], v[218:219]
	v_pk_add_f32 v[228:229], v[228:229], v[218:219]
	v_pk_add_f32 v[230:231], v[230:231], v[218:219]
	v_rcp_f32_e32 v224, v224
	v_rcp_f32_e32 v225, v225
	v_rcp_f32_e32 v226, v226
	v_rcp_f32_e32 v227, v227
	v_rcp_f32_e32 v228, v228
	v_rcp_f32_e32 v229, v229
	v_rcp_f32_e32 v230, v230
	v_rcp_f32_e32 v231, v231
	v_pk_mul_f32 v[232:233], v[232:233], v[222:223] op_sel_hi:[1,0]
	v_pk_mul_f32 v[234:235], v[234:235], v[222:223] op_sel_hi:[1,0]
	v_pk_mul_f32 v[236:237], v[236:237], v[222:223] op_sel_hi:[1,0]
	v_pk_mul_f32 v[238:239], v[238:239], v[222:223] op_sel_hi:[1,0]
	v_pk_mul_f32 v[232:233], v[232:233], v[224:225]
	v_pk_mul_f32 v[234:235], v[234:235], v[226:227]
	v_pk_mul_f32 v[236:237], v[236:237], v[228:229]
	v_pk_mul_f32 v[238:239], v[238:239], v[230:231]
	v_cvt_pk_bf16_f32 v244, v232, v233
	v_cvt_pk_bf16_f32 v245, v234, v235
	v_cvt_pk_bf16_f32 v246, v236, v237
	v_cvt_pk_bf16_f32 v247, v238, v239
	global_store_dwordx4 v[250:251], v[244:247], off
	v_mul_f32_e32 v220, 0xbfb8aa3b, v142
	v_mul_f32_e32 v222, v142, v142
	v_pk_mul_f32 v[224:225], v[100:101], v[220:221] op_sel_hi:[1,0]
	v_pk_mul_f32 v[226:227], v[102:103], v[220:221] op_sel_hi:[1,0]
	v_pk_mul_f32 v[228:229], v[92:93], v[220:221] op_sel_hi:[1,0]
	v_pk_mul_f32 v[230:231], v[94:95], v[220:221] op_sel_hi:[1,0]
	v_mad_u64_u32 v[250:251], s[8:9], v196, s13, v[248:249]
	v_exp_f32_e32 v224, v224
	v_exp_f32_e32 v225, v225
	v_exp_f32_e32 v226, v226
	v_exp_f32_e32 v227, v227
	v_exp_f32_e32 v228, v228
	v_exp_f32_e32 v229, v229
	v_exp_f32_e32 v230, v230
	v_exp_f32_e32 v231, v231
	v_pk_mul_f32 v[232:233], v[100:101], v[96:97]
	v_pk_mul_f32 v[234:235], v[102:103], v[98:99]
	v_pk_mul_f32 v[236:237], v[92:93], v[88:89]
	v_pk_mul_f32 v[238:239], v[94:95], v[90:91]
	v_pk_add_f32 v[224:225], v[224:225], v[218:219]
	v_pk_add_f32 v[226:227], v[226:227], v[218:219]
	v_pk_add_f32 v[228:229], v[228:229], v[218:219]
	v_pk_add_f32 v[230:231], v[230:231], v[218:219]
	v_rcp_f32_e32 v224, v224
	v_rcp_f32_e32 v225, v225
	v_rcp_f32_e32 v226, v226
	v_rcp_f32_e32 v227, v227
	v_rcp_f32_e32 v228, v228
	v_rcp_f32_e32 v229, v229
	v_rcp_f32_e32 v230, v230
	v_rcp_f32_e32 v231, v231
	v_pk_mul_f32 v[232:233], v[232:233], v[222:223] op_sel_hi:[1,0]
	v_pk_mul_f32 v[234:235], v[234:235], v[222:223] op_sel_hi:[1,0]
	v_pk_mul_f32 v[236:237], v[236:237], v[222:223] op_sel_hi:[1,0]
	v_pk_mul_f32 v[238:239], v[238:239], v[222:223] op_sel_hi:[1,0]
	v_pk_mul_f32 v[232:233], v[232:233], v[224:225]
	v_pk_mul_f32 v[234:235], v[234:235], v[226:227]
	v_pk_mul_f32 v[236:237], v[236:237], v[228:229]
	v_pk_mul_f32 v[238:239], v[238:239], v[230:231]
	v_cvt_pk_bf16_f32 v240, v232, v233
; __device__ __forceinline__ unsigned cvt_pk_bf16(float lo, float hi) { bf16v2_t r = __builtin_convertvector((f32x2_t){lo, hi}, bf16v2_t); return __builtin_bit_cast(unsigned, r); }
; __device__ __forceinline__ float sigm(float x) { return __builtin_amdgcn_rcpf(1.0f + __expf(-x)); }
;     __device__ __forceinline__ void operator()(const f32x4 (&acc)[2][2][4][2], const Unit& u, int wr, int wc, int fr, int fq) const {
;     ...
;             for (int m = 0; m < 4; ++m) {
;                 bf16_t* rowp = O + (size_t)(row0 + ai * HALF + m * 16) * ldc + col0;
;                 const float ri = rr.get(ai, m);
;                 float r[8];
; #pragma unroll
;                 for (int n = 0; n < 2; ++n)
; #pragma unroll
;                     for (int j = 0; j < 4; ++j) { const float g = acc[ai][0][m][n][j] * ri, up = acc[ai][1][m][n][j] * ri; r[n * 4 + j] = g * sigm(g) * up; }
;                 u32x4 w; w.x = cvt_pk_bf16(r[0], r[1]); w.y = cvt_pk_bf16(r[2], r[3]); w.z = cvt_pk_bf16(r[4], r[5]); w.w = cvt_pk_bf16(r[6], r[7]);
;                 *(u32x4*)rowp = w;
	v_cvt_pk_bf16_f32 v241, v234, v235
	v_cvt_pk_bf16_f32 v242, v236, v237
	v_cvt_pk_bf16_f32 v243, v238, v239
	global_store_dwordx4 v[250:251], v[240:243], off
	v_mul_f32_e32 v220, 0xbfb8aa3b, v146
	v_mul_f32_e32 v222, v146, v146
	v_pk_mul_f32 v[224:225], v[84:85], v[220:221] op_sel_hi:[1,0]
	v_pk_mul_f32 v[226:227], v[86:87], v[220:221] op_sel_hi:[1,0]
	v_pk_mul_f32 v[228:229], v[76:77], v[220:221] op_sel_hi:[1,0]
	v_pk_mul_f32 v[230:231], v[78:79], v[220:221] op_sel_hi:[1,0]
	v_mad_u64_u32 v[250:251], s[8:9], v194, s13, v[248:249]
	v_exp_f32_e32 v224, v224
	v_exp_f32_e32 v225, v225
	v_exp_f32_e32 v226, v226
	v_exp_f32_e32 v227, v227
	v_exp_f32_e32 v228, v228
	v_exp_f32_e32 v229, v229
	v_exp_f32_e32 v230, v230
	v_exp_f32_e32 v231, v231
	v_pk_mul_f32 v[232:233], v[84:85], v[80:81]
	v_pk_mul_f32 v[234:235], v[86:87], v[82:83]
	v_pk_mul_f32 v[236:237], v[76:77], v[72:73]
	v_pk_mul_f32 v[238:239], v[78:79], v[74:75]
	v_pk_add_f32 v[224:225], v[224:225], v[218:219]
	v_pk_add_f32 v[226:227], v[226:227], v[218:219]
	v_pk_add_f32 v[228:229], v[228:229], v[218:219]
	v_pk_add_f32 v[230:231], v[230:231], v[218:219]
	v_rcp_f32_e32 v224, v224
	v_rcp_f32_e32 v225, v225
	v_rcp_f32_e32 v226, v226
	v_rcp_f32_e32 v227, v227
	v_rcp_f32_e32 v228, v228
	v_rcp_f32_e32 v229, v229
	v_rcp_f32_e32 v230, v230
	v_rcp_f32_e32 v231, v231
	v_pk_mul_f32 v[232:233], v[232:233], v[222:223] op_sel_hi:[1,0]
	v_pk_mul_f32 v[234:235], v[234:235], v[222:223] op_sel_hi:[1,0]
	v_pk_mul_f32 v[236:237], v[236:237], v[222:223] op_sel_hi:[1,0]
	v_pk_mul_f32 v[238:239], v[238:239], v[222:223] op_sel_hi:[1,0]
	v_pk_mul_f32 v[232:233], v[232:233], v[224:225]
	v_pk_mul_f32 v[234:235], v[234:235], v[226:227]
	v_pk_mul_f32 v[236:237], v[236:237], v[228:229]
	v_pk_mul_f32 v[238:239], v[238:239], v[230:231]
	v_cvt_pk_bf16_f32 v244, v232, v233
	v_cvt_pk_bf16_f32 v245, v234, v235
	v_cvt_pk_bf16_f32 v246, v236, v237
	v_cvt_pk_bf16_f32 v247, v238, v239
	global_store_dwordx4 v[250:251], v[244:247], off
	v_mul_f32_e32 v220, 0xbfb8aa3b, v104
	v_mul_f32_e32 v222, v104, v104
	v_pk_mul_f32 v[224:225], v[68:69], v[220:221] op_sel_hi:[1,0]
	v_pk_mul_f32 v[226:227], v[70:71], v[220:221] op_sel_hi:[1,0]
	v_pk_mul_f32 v[228:229], v[60:61], v[220:221] op_sel_hi:[1,0]
	v_pk_mul_f32 v[230:231], v[62:63], v[220:221] op_sel_hi:[1,0]
	v_mad_u64_u32 v[250:251], s[8:9], v192, s13, v[248:249]
	v_exp_f32_e32 v224, v224
	v_exp_f32_e32 v225, v225
	v_exp_f32_e32 v226, v226
	v_exp_f32_e32 v227, v227
	v_exp_f32_e32 v228, v228
	v_exp_f32_e32 v229, v229
	v_exp_f32_e32 v230, v230
	v_exp_f32_e32 v231, v231
	v_pk_mul_f32 v[232:233], v[68:69], v[64:65]
	v_pk_mul_f32 v[234:235], v[70:71], v[66:67]
	v_pk_mul_f32 v[236:237], v[60:61], v[56:57]
	v_pk_mul_f32 v[238:239], v[62:63], v[58:59]
	v_pk_add_f32 v[224:225], v[224:225], v[218:219]
	v_pk_add_f32 v[226:227], v[226:227], v[218:219]
	v_pk_add_f32 v[228:229], v[228:229], v[218:219]
	v_pk_add_f32 v[230:231], v[230:231], v[218:219]
	v_rcp_f32_e32 v224, v224
	v_rcp_f32_e32 v225, v225
	v_rcp_f32_e32 v226, v226
	v_rcp_f32_e32 v227, v227
	v_rcp_f32_e32 v228, v228
	v_rcp_f32_e32 v229, v229
	v_rcp_f32_e32 v230, v230
	v_rcp_f32_e32 v231, v231
	v_pk_mul_f32 v[232:233], v[232:233], v[222:223] op_sel_hi:[1,0]
	v_pk_mul_f32 v[234:235], v[234:235], v[222:223] op_sel_hi:[1,0]
	v_pk_mul_f32 v[236:237], v[236:237], v[222:223] op_sel_hi:[1,0]
	v_pk_mul_f32 v[238:239], v[238:239], v[222:223] op_sel_hi:[1,0]
	v_pk_mul_f32 v[232:233], v[232:233], v[224:225]
	v_pk_mul_f32 v[234:235], v[234:235], v[226:227]
	v_pk_mul_f32 v[236:237], v[236:237], v[228:229]
	v_pk_mul_f32 v[238:239], v[238:239], v[230:231]
	v_cvt_pk_bf16_f32 v240, v232, v233
	v_cvt_pk_bf16_f32 v241, v234, v235
	v_cvt_pk_bf16_f32 v242, v236, v237
	v_cvt_pk_bf16_f32 v243, v238, v239
	global_store_dwordx4 v[250:251], v[240:243], off
	v_mul_f32_e32 v220, 0xbfb8aa3b, v144
	v_mul_f32_e32 v222, v144, v144
	v_add_u32_e32 v216, 16, v192
	v_pk_mul_f32 v[224:225], v[52:53], v[220:221] op_sel_hi:[1,0]
	v_pk_mul_f32 v[226:227], v[54:55], v[220:221] op_sel_hi:[1,0]
	v_pk_mul_f32 v[228:229], v[44:45], v[220:221] op_sel_hi:[1,0]
	v_pk_mul_f32 v[230:231], v[46:47], v[220:221] op_sel_hi:[1,0]
	v_mad_u64_u32 v[250:251], s[8:9], v216, s13, v[248:249]
	v_exp_f32_e32 v224, v224
	v_exp_f32_e32 v225, v225
	v_exp_f32_e32 v226, v226
	v_exp_f32_e32 v227, v227
	v_exp_f32_e32 v228, v228
	v_exp_f32_e32 v229, v229
	v_exp_f32_e32 v230, v230
	v_exp_f32_e32 v231, v231
	v_pk_mul_f32 v[232:233], v[52:53], v[48:49]
	v_pk_mul_f32 v[234:235], v[54:55], v[50:51]
	v_pk_mul_f32 v[236:237], v[44:45], v[40:41]
	v_pk_mul_f32 v[238:239], v[46:47], v[42:43]
	v_pk_add_f32 v[224:225], v[224:225], v[218:219]
	v_pk_add_f32 v[226:227], v[226:227], v[218:219]
	v_pk_add_f32 v[228:229], v[228:229], v[218:219]
; __device__ __forceinline__ unsigned cvt_pk_bf16(float lo, float hi) { bf16v2_t r = __builtin_convertvector((f32x2_t){lo, hi}, bf16v2_t); return __builtin_bit_cast(unsigned, r); }
; #define PG8_BAR __builtin_amdgcn_s_barrier()
; __device__ __forceinline__ float sigm(float x) { return __builtin_amdgcn_rcpf(1.0f + __expf(-x)); }
; template <class Epi, class Sched, bool ALIGN_EPI = false, bool SP2 = false>
; __device__ __forceinline__ void gemm_phase(PG8_LAS unsigned char* lds, const Gemm g, const Sched& S, const Epi& E) {
;     ...
;         if constexpr (!Epi::AFTER_DRAIN) { if (wr == 0) __builtin_amdgcn_s_setprio(1);
;             E(acc, cur, wr, wc, fr, fq); __builtin_amdgcn_s_setprio(0); S.done(cur); }
;         if (!has_next) break;
; #pragma unroll
;         for (int a = 0; a < 2; ++a)
; #pragma unroll
;             for (int b = 0; b < 2; ++b)
; #pragma unroll
;                 for (int m = 0; m < 4; ++m)
; #pragma unroll
;                     for (int n = 0; n < 2; ++n) acc[a][b][m][n] = (f32x4){0.f, 0.f, 0.f, 0.f};
;         cur = nxt; cA = nA; cB = nB; ++ui;
;         if constexpr (ALIGN_EPI) { if (wr == 1) PG8_BAR; }
;     }
;     __device__ __forceinline__ void operator()(const f32x4 (&acc)[2][2][4][2], const Unit& u, int wr, int wc, int fr, int fq) const {
;     ...
;                 bf16_t* rowp = O + (size_t)(row0 + ai * HALF + m * 16) * ldc + col0;
;                 const float ri = rr.get(ai, m);
;                 float r[8];
; #pragma unroll
;                 for (int n = 0; n < 2; ++n)
; #pragma unroll
;                     for (int j = 0; j < 4; ++j) { const float g = acc[ai][0][m][n][j] * ri, up = acc[ai][1][m][n][j] * ri; r[n * 4 + j] = g * sigm(g) * up; }
;                 u32x4 w; w.x = cvt_pk_bf16(r[0], r[1]); w.y = cvt_pk_bf16(r[2], r[3]); w.z = cvt_pk_bf16(r[4], r[5]); w.w = cvt_pk_bf16(r[6], r[7]);
;                 *(u32x4*)rowp = w;
	v_pk_add_f32 v[230:231], v[230:231], v[218:219]
	v_rcp_f32_e32 v224, v224
	v_rcp_f32_e32 v225, v225
	v_rcp_f32_e32 v226, v226
	v_rcp_f32_e32 v227, v227
	v_rcp_f32_e32 v228, v228
	v_rcp_f32_e32 v229, v229
	v_rcp_f32_e32 v230, v230
	v_rcp_f32_e32 v231, v231
	v_pk_mul_f32 v[232:233], v[232:233], v[222:223] op_sel_hi:[1,0]
	v_pk_mul_f32 v[234:235], v[234:235], v[222:223] op_sel_hi:[1,0]
	v_pk_mul_f32 v[236:237], v[236:237], v[222:223] op_sel_hi:[1,0]
	v_pk_mul_f32 v[238:239], v[238:239], v[222:223] op_sel_hi:[1,0]
	v_pk_mul_f32 v[232:233], v[232:233], v[224:225]
	v_pk_mul_f32 v[234:235], v[234:235], v[226:227]
	v_pk_mul_f32 v[236:237], v[236:237], v[228:229]
	v_pk_mul_f32 v[238:239], v[238:239], v[230:231]
	v_cvt_pk_bf16_f32 v244, v232, v233
	v_cvt_pk_bf16_f32 v245, v234, v235
	v_cvt_pk_bf16_f32 v246, v236, v237
	v_cvt_pk_bf16_f32 v247, v238, v239
	global_store_dwordx4 v[250:251], v[244:247], off
	v_mul_f32_e32 v220, 0xbfb8aa3b, v106
	v_mul_f32_e32 v222, v106, v106
	v_add_u32_e32 v216, 32, v192
	v_pk_mul_f32 v[224:225], v[36:37], v[220:221] op_sel_hi:[1,0]
	v_pk_mul_f32 v[226:227], v[38:39], v[220:221] op_sel_hi:[1,0]
	v_pk_mul_f32 v[228:229], v[28:29], v[220:221] op_sel_hi:[1,0]
	v_pk_mul_f32 v[230:231], v[30:31], v[220:221] op_sel_hi:[1,0]
	v_mad_u64_u32 v[250:251], s[8:9], v216, s13, v[248:249]
	v_exp_f32_e32 v224, v224
	v_exp_f32_e32 v225, v225
	v_exp_f32_e32 v226, v226
	v_exp_f32_e32 v227, v227
	v_exp_f32_e32 v228, v228
	v_exp_f32_e32 v229, v229
	v_exp_f32_e32 v230, v230
	v_exp_f32_e32 v231, v231
	v_pk_mul_f32 v[232:233], v[36:37], v[32:33]
	v_pk_mul_f32 v[234:235], v[38:39], v[34:35]
	v_pk_mul_f32 v[236:237], v[28:29], v[24:25]
	v_pk_mul_f32 v[238:239], v[30:31], v[26:27]
	v_pk_add_f32 v[224:225], v[224:225], v[218:219]
	v_pk_add_f32 v[226:227], v[226:227], v[218:219]
	v_pk_add_f32 v[228:229], v[228:229], v[218:219]
	v_pk_add_f32 v[230:231], v[230:231], v[218:219]
	v_rcp_f32_e32 v224, v224
	v_rcp_f32_e32 v225, v225
	v_rcp_f32_e32 v226, v226
	v_rcp_f32_e32 v227, v227
	v_rcp_f32_e32 v228, v228
	v_rcp_f32_e32 v229, v229
	v_rcp_f32_e32 v230, v230
	v_rcp_f32_e32 v231, v231
	v_pk_mul_f32 v[232:233], v[232:233], v[222:223] op_sel_hi:[1,0]
	v_pk_mul_f32 v[234:235], v[234:235], v[222:223] op_sel_hi:[1,0]
	v_pk_mul_f32 v[236:237], v[236:237], v[222:223] op_sel_hi:[1,0]
	v_pk_mul_f32 v[238:239], v[238:239], v[222:223] op_sel_hi:[1,0]
	v_pk_mul_f32 v[232:233], v[232:233], v[224:225]
	v_pk_mul_f32 v[234:235], v[234:235], v[226:227]
	v_pk_mul_f32 v[236:237], v[236:237], v[228:229]
	v_pk_mul_f32 v[238:239], v[238:239], v[230:231]
	v_cvt_pk_bf16_f32 v240, v232, v233
	v_cvt_pk_bf16_f32 v241, v234, v235
	v_cvt_pk_bf16_f32 v242, v236, v237
	v_cvt_pk_bf16_f32 v243, v238, v239
	global_store_dwordx4 v[250:251], v[240:243], off
	v_mul_f32_e32 v220, 0xbfb8aa3b, v0
	v_mul_f32_e32 v222, v0, v0
	v_add_u32_e32 v216, 48, v192
	v_pk_mul_f32 v[224:225], v[20:21], v[220:221] op_sel_hi:[1,0]
	v_pk_mul_f32 v[226:227], v[22:23], v[220:221] op_sel_hi:[1,0]
	v_pk_mul_f32 v[228:229], v[12:13], v[220:221] op_sel_hi:[1,0]
	v_pk_mul_f32 v[230:231], v[14:15], v[220:221] op_sel_hi:[1,0]
	v_mad_u64_u32 v[250:251], s[8:9], v216, s13, v[248:249]
	v_exp_f32_e32 v224, v224
	v_exp_f32_e32 v225, v225
	v_exp_f32_e32 v226, v226
	v_exp_f32_e32 v227, v227
	v_exp_f32_e32 v228, v228
	v_exp_f32_e32 v229, v229
	v_exp_f32_e32 v230, v230
	v_exp_f32_e32 v231, v231
	v_pk_mul_f32 v[232:233], v[20:21], v[16:17]
	v_pk_mul_f32 v[234:235], v[22:23], v[18:19]
	v_pk_mul_f32 v[236:237], v[12:13], v[8:9]
	v_pk_mul_f32 v[238:239], v[14:15], v[10:11]
	v_pk_add_f32 v[224:225], v[224:225], v[218:219]
	v_pk_add_f32 v[226:227], v[226:227], v[218:219]
	v_pk_add_f32 v[228:229], v[228:229], v[218:219]
	v_pk_add_f32 v[230:231], v[230:231], v[218:219]
	v_rcp_f32_e32 v224, v224
	v_rcp_f32_e32 v225, v225
	v_rcp_f32_e32 v226, v226
	v_rcp_f32_e32 v227, v227
	v_rcp_f32_e32 v228, v228
	v_rcp_f32_e32 v229, v229
	v_rcp_f32_e32 v230, v230
	v_rcp_f32_e32 v231, v231
	v_pk_mul_f32 v[232:233], v[232:233], v[222:223] op_sel_hi:[1,0]
	v_pk_mul_f32 v[234:235], v[234:235], v[222:223] op_sel_hi:[1,0]
	v_pk_mul_f32 v[236:237], v[236:237], v[222:223] op_sel_hi:[1,0]
	v_pk_mul_f32 v[238:239], v[238:239], v[222:223] op_sel_hi:[1,0]
	v_pk_mul_f32 v[232:233], v[232:233], v[224:225]
	v_pk_mul_f32 v[234:235], v[234:235], v[226:227]
	v_pk_mul_f32 v[236:237], v[236:237], v[228:229]
	v_pk_mul_f32 v[238:239], v[238:239], v[230:231]
	v_cvt_pk_bf16_f32 v244, v232, v233
	v_cvt_pk_bf16_f32 v245, v234, v235
	v_cvt_pk_bf16_f32 v246, v236, v237
	v_cvt_pk_bf16_f32 v247, v238, v239
	global_store_dwordx4 v[250:251], v[244:247], off
	s_setprio 0
	s_andn2_b64 vcc, exec, s[6:7]
	s_mov_b64 s[6:7], -1
	s_cbranch_vccnz .LBB0_253
	s_andn2_b64 vcc, exec, s[2:3]
	s_cbranch_vccnz .LBB0_252
	s_barrier
	s_branch .LBB0_252
